# speedup vs baseline: 1.0083x; 1.0004x over previous
; __device__ __forceinline__ void finishSM(f32x16& p0, f32x16& p1, float alpha, float& l_reg, bf16x8& pa0, bf16x8& pa1, bf16x8& pa2, bf16x8& pa3) {
; #pragma unroll
;   for (int r = 0; r < 16; ++r) p1[r] = __builtin_amdgcn_exp2f(p1[r]);
;   float ps = 0;
; #pragma unroll
;   for (int r = 0; r < 16; ++r) ps += p0[r];
; #pragma unroll
;   for (int r = 0; r < 16; ++r) ps += p1[r];
;   { auto rr = __builtin_amdgcn_permlane32_swap(__float_as_uint(ps), __float_as_uint(ps), false, false);
;     ps = __uint_as_float(rr[0]) + __uint_as_float(rr[1]); }
;   l_reg = l_reg * alpha + ps;
;     ...
;   PK4(p0, 0, pa0); PK4(p0, 8, pa1); PK4(p1, 0, pa2); PK4(p1, 8, pa3);
;     ...
; }
; #pragma unroll
;   for (int r = 0; r < 16; ++r) { p0[r] = init; p1[r] = init; }
; #pragma unroll
;   for (int d0 = 0; d0 < 8; ++d0) { int cb = (d0 * 16 + hi * 8) * 2;
;     bf16x8 b0 = *reinterpret_cast<const bf16x8*>((const char*)Ks + KSWZ(r32, cb));
;     bf16x8 b1 = *reinterpret_cast<const bf16x8*>((const char*)Ks + KSWZ(32 + r32, cb));
;     p0 = __builtin_amdgcn_mfma_f32_32x32x16_bf16(b0, qr[d0], p0, 0, 0, 0);
;     p1 = __builtin_amdgcn_mfma_f32_32x32x16_bf16(b1, qr[d0], p1, 0, 0, 0); }
; }
; __device__ __forceinline__ void qkt_c(f32x16& p0, f32x16& p1, const bf16* Ks, const bf16x8* qr, int r32, int hi) {
;   const f32x16 cinit = {};
; #pragma unroll
;   for (int d0 = 0; d0 < 8; ++d0) { int cb = (d0 * 16 + hi * 8) * 2;
;     bf16x8 b0 = *reinterpret_cast<const bf16x8*>((const char*)Ks + KSWZ(r32, cb));
;     bf16x8 b1 = *reinterpret_cast<const bf16x8*>((const char*)Ks + KSWZ(32 + r32, cb));
;     p0 = __builtin_amdgcn_mfma_f32_32x32x16_bf16(b0, qr[d0], d0 == 0 ? cinit : p0, 0, 0, 0);
;     p1 = __builtin_amdgcn_mfma_f32_32x32x16_bf16(b1, qr[d0], d0 == 0 ? cinit : p1, 0, 0, 0); }
; }
.LBB0_118:
	s_add_i32 s2, s2, 2
	ds_read_b128 v[10:13], v201 offset:49152
	ds_read_b128 v[176:179], v201 offset:57344
	ds_read_b128 v[188:191], v202 offset:49152
	ds_read_b128 v[192:195], v202 offset:57344
	v_exp_f32_e32 v88, v88
	v_exp_f32_e32 v89, v89
	v_exp_f32_e32 v90, v90
	v_exp_f32_e32 v91, v91
	v_exp_f32_e32 v92, v92
	v_exp_f32_e32 v93, v93
	v_exp_f32_e32 v94, v94
	v_exp_f32_e32 v95, v95
	s_waitcnt lgkmcnt(5)
	v_mfma_f32_32x32x16_bf16 v[112:127], v[2:5], v[156:159], 0
	s_waitcnt lgkmcnt(4)
	v_mfma_f32_32x32x16_bf16 v[96:111], v[6:9], v[156:159], 0
	ds_read_b128 v[2:5], v203 offset:49152
	ds_read_b128 v[6:9], v203 offset:57344
	s_waitcnt lgkmcnt(5)
	v_mfma_f32_32x32x16_bf16 v[112:127], v[10:13], v[152:155], v[112:127]
	s_waitcnt lgkmcnt(4)
	v_mfma_f32_32x32x16_bf16 v[96:111], v[176:179], v[152:155], v[96:111]
	ds_read_b128 v[10:13], v206 offset:49152
	ds_read_b128 v[176:179], v206 offset:57344
	s_waitcnt lgkmcnt(5)
	v_mfma_f32_32x32x16_bf16 v[112:127], v[188:191], v[148:151], v[112:127]
	s_waitcnt lgkmcnt(4)
	v_mfma_f32_32x32x16_bf16 v[96:111], v[192:195], v[148:151], v[96:111]
	ds_read_b128 v[188:191], v204 offset:49152
	ds_read_b128 v[192:195], v204 offset:57344
	s_waitcnt lgkmcnt(5)
	v_mfma_f32_32x32x16_bf16 v[112:127], v[2:5], v[144:147], v[112:127]
	s_waitcnt lgkmcnt(4)
	v_mfma_f32_32x32x16_bf16 v[96:111], v[6:9], v[144:147], v[96:111]
	ds_read_b128 v[2:5], v205 offset:49152
	ds_read_b128 v[6:9], v205 offset:57344
	v_add_u32_e32 v254, vcc_lo, v184
	v_add_u32_e32 v255, vcc_lo, v185
	s_waitcnt vmcnt(0)
	ds_write_b128 v254, v[160:163]
	s_waitcnt lgkmcnt(6)
	v_mfma_f32_32x32x16_bf16 v[112:127], v[10:13], v[140:143], v[112:127]
	s_waitcnt lgkmcnt(5)
	v_mfma_f32_32x32x16_bf16 v[96:111], v[176:179], v[140:143], v[96:111]
	ds_read_b128 v[10:13], v207 offset:49152
	ds_read_b128 v[176:179], v207 offset:57344
	ds_write_b128 v255, v[164:167]
	s_waitcnt lgkmcnt(7)
	v_mfma_f32_32x32x16_bf16 v[112:127], v[188:191], v[136:139], v[112:127]
	s_waitcnt lgkmcnt(6)
	v_mfma_f32_32x32x16_bf16 v[96:111], v[192:195], v[136:139], v[96:111]
	ds_write_b128 v198, v[168:171] offset:32768
	s_waitcnt lgkmcnt(6)
	v_mfma_f32_32x32x16_bf16 v[112:127], v[2:5], v[132:135], v[112:127]
	s_waitcnt lgkmcnt(5)
	v_mfma_f32_32x32x16_bf16 v[96:111], v[6:9], v[132:135], v[96:111]
	ds_write_b128 v199, v[172:175] offset:32768
	s_waitcnt lgkmcnt(4)
	v_mfma_f32_32x32x16_bf16 v[112:127], v[10:13], v[128:131], v[112:127]
	s_waitcnt lgkmcnt(3)
	v_mfma_f32_32x32x16_bf16 v[96:111], v[176:179], v[128:131], v[96:111]
	v_exp_f32_e32 v2, v80
	v_add_f32_e32 v80, 0, v223
	v_add_f32_e32 v80, v225, v80
	v_add_f32_e32 v80, v221, v80
	v_add_f32_e32 v80, v224, v80
	v_add_f32_e32 v80, v220, v80
	v_add_f32_e32 v80, v222, v80
	v_add_f32_e32 v80, v218, v80
	v_add_f32_e32 v80, v219, v80
	v_add_f32_e32 v80, v215, v80
	v_add_f32_e32 v80, v217, v80
	v_add_f32_e32 v80, v214, v80
	v_add_f32_e32 v80, v216, v80
	v_add_f32_e32 v80, v210, v80
	v_exp_f32_e32 v3, v81
	v_add_f32_e32 v80, v213, v80
	v_exp_f32_e32 v4, v82
	v_add_f32_e32 v80, v211, v80
	v_exp_f32_e32 v5, v83
	v_add_f32_e32 v80, v212, v80
	v_exp_f32_e32 v6, v84
	v_add_f32_e32 v80, v2, v80
	v_exp_f32_e32 v7, v85
	v_add_f32_e32 v80, v3, v80
	v_exp_f32_e32 v8, v86
	v_add_f32_e32 v80, v4, v80
	v_exp_f32_e32 v9, v87
	v_add_f32_e32 v80, v5, v80
	v_add_f32_e32 v80, v6, v80
	v_add_f32_e32 v80, v7, v80
	v_add_f32_e32 v80, v8, v80
	v_add_f32_e32 v80, v9, v80
	v_add_f32_e32 v80, v88, v80
	v_add_f32_e32 v80, v89, v80
	v_add_f32_e32 v80, v90, v80
	v_add_f32_e32 v80, v91, v80
	v_add_f32_e32 v80, v92, v80
	v_add_f32_e32 v80, v93, v80
	v_add_f32_e32 v80, v94, v80
	v_add_f32_e32 v80, v95, v80
	v_mov_b32_e32 v81, v80
	s_nop 1
	v_permlane32_swap_b32_e32 v80, v81
	v_add_f32_e32 v80, v80, v81
	v_add_f32_e32 v226, v183, v80
	v_cvt_pk_bf16_f32 v80, v223, v225
	v_cvt_pk_bf16_f32 v81, v221, v224
	v_cvt_pk_bf16_f32 v82, v220, v222
	v_cvt_pk_bf16_f32 v83, v218, v219
	v_cvt_pk_bf16_f32 v84, v215, v217
	v_cvt_pk_bf16_f32 v85, v214, v216
	v_cvt_pk_bf16_f32 v86, v210, v213
	v_cvt_pk_bf16_f32 v87, v211, v212
	v_cvt_pk_bf16_f32 v95, v94, v95
	v_cvt_pk_bf16_f32 v94, v92, v93
	v_cvt_pk_bf16_f32 v93, v90, v91
	v_cvt_pk_bf16_f32 v92, v88, v89
	v_cvt_pk_bf16_f32 v88, v2, v3
	v_cvt_pk_bf16_f32 v89, v4, v5
	v_cvt_pk_bf16_f32 v90, v6, v7
	v_cvt_pk_bf16_f32 v91, v8, v9
	v_permlane32_swap_b32_e32 v80, v82
	v_permlane32_swap_b32_e32 v81, v83
	v_permlane32_swap_b32_e32 v84, v86
	v_permlane32_swap_b32_e32 v85, v87
	v_permlane32_swap_b32_e32 v88, v90
	v_permlane32_swap_b32_e32 v89, v91
	v_permlane32_swap_b32_e32 v93, v95
	v_permlane32_swap_b32_e32 v92, v94
	s_add_i32 s100, s2, 2
	s_mul_i32 s100, s100, 0x60000
	v_add_u32_e32 v254, s100, v14
	v_add_u32_e32 v255, s100, v15
	global_load_dwordx4 v[2:5], v254, s[58:59]
	global_load_dwordx4 v[6:9], v255, s[58:59]
	global_load_dwordx4 v[10:13], v254, s[8:9]
	global_load_dwordx4 v[176:179], v255, s[8:9]
	v_add_u32_e32 v255, vcc_hi, v208
	ds_read_b64_tr_b16 v[210:211], v255 offset:0
	ds_read_b64_tr_b16 v[212:213], v255 offset:0x800
	ds_read_b64_tr_b16 v[214:215], v255 offset:0x1000
	ds_read_b64_tr_b16 v[216:217], v255 offset:0x1800
	ds_read_b64_tr_b16 v[218:219], v255 offset:0x2000
	ds_read_b64_tr_b16 v[220:221], v255 offset:0x2800
	ds_read_b64_tr_b16 v[222:223], v255 offset:0x3000
	ds_read_b64_tr_b16 v[224:225], v255 offset:0x3800
	s_waitcnt lgkmcnt(0)
; #define SBAR() __builtin_amdgcn_sched_barrier(0)
; #define SWAIT() asm volatile("s_waitcnt vmcnt(4)" ::: "memory")
; #define RESC(a) do { if (!FIXED && __any((a) < 1.f)) { if (hi == 0) al_l[r32] = (a); asm volatile("s_waitcnt lgkmcnt(0)" ::: "memory"); \
;     _Pragma("unroll") for (int d = 0; d < 4; ++d) _Pragma("unroll") for (int r = 0; r < 16; ++r) o[d][r] *= al_l[crow(r, hi)]; } } while (0)
; #define MASK(P0, P1, t) do { if (BANDED) band_mask(P0, P1, rel00 + (t) * KVBLK, mlo, mhi); } while (0)
; template <int D0> __device__ __forceinline__ void pv_one(f32x16& od, int vb, bf16x8 pa0, bf16x8 pa1, bf16x8 pa2, bf16x8 pa3) {
;   const s16x4 l0 = tr_read<v_rd_off(D0, 0, 0)>(vb), h0 = tr_read<v_rd_off(D0, 0, 1)>(vb), l1 = tr_read<v_rd_off(D0, 1, 0)>(vb), h1 = tr_read<v_rd_off(D0, 1, 1)>(vb);
;   const s16x4 l2 = tr_read<v_rd_off(D0, 2, 0)>(vb), h2 = tr_read<v_rd_off(D0, 2, 1)>(vb), l3 = tr_read<v_rd_off(D0, 3, 0)>(vb), h3 = tr_read<v_rd_off(D0, 3, 1)>(vb);
;   asm volatile("s_waitcnt lgkmcnt(0)" ::: "memory"); SBAR();
;     ...
;   od = __builtin_amdgcn_mfma_f32_32x32x16_bf16(pa0, PK(l0, h0), od, 0, 0, 0);
;   od = __builtin_amdgcn_mfma_f32_32x32x16_bf16(pa1, PK(l1, h1), od, 0, 0, 0);
;   od = __builtin_amdgcn_mfma_f32_32x32x16_bf16(pa2, PK(l2, h2), od, 0, 0, 0);
;   od = __builtin_amdgcn_mfma_f32_32x32x16_bf16(pa3, PK(l3, h3), od, 0, 0, 0);
;     ...
; }
; __device__ __forceinline__ void pv_d0(f32x16* o, int vb, bf16x8 pa0, bf16x8 pa1, bf16x8 pa2, bf16x8 pa3) {
;   pv_one<0>(o[0], vb, pa0, pa1, pa2, pa3); pv_one<1>(o[1], vb, pa0, pa1, pa2, pa3); pv_one<2>(o[2], vb, pa0, pa1, pa2, pa3); pv_one<3>(o[3], vb, pa0, pa1, pa2, pa3);
; template <bool BANDED, bool FIXED> ...
;     ...
;     pv_d0(o, vb0, pa0, pa1, pa2, pa3); partialSM<FIXED, !BANDED>(pB0, pB1, m_reg, mnB, alB);
;     __syncthreads(); SWAIT(); SWRITE(0, SE);
;     RESC(alB); __syncthreads();
;     SBAR(); if (FIXED) qkt_c(pA0, pA1, K_lds, qr, r32, hi); else qkt(pA0, pA1, K_lds, qr, r32, hi, 0.f); MASK(pA0, pA1, j + 1);
;     finishSM(pB0, pB1, alB, l_reg, pa0, pa1, pa2, pa3); SBAR();
	s_nop 0
	v_mfma_f32_32x32x16_bf16 v[16:31], v[80:83], v[210:213], v[16:31]
	ds_read_b64_tr_b16 v[210:211], v255 offset:0x200
	ds_read_b64_tr_b16 v[212:213], v255 offset:0xa00
	v_mfma_f32_32x32x16_bf16 v[16:31], v[84:87], v[214:217], v[16:31]
	ds_read_b64_tr_b16 v[214:215], v255 offset:0x1200
	ds_read_b64_tr_b16 v[216:217], v255 offset:0x1a00
	v_mfma_f32_32x32x16_bf16 v[16:31], v[88:91], v[218:221], v[16:31]
	ds_read_b64_tr_b16 v[218:219], v255 offset:0x2200
	ds_read_b64_tr_b16 v[220:221], v255 offset:0x2a00
	v_mfma_f32_32x32x16_bf16 v[16:31], v[92:95], v[222:225], v[16:31]
	ds_read_b64_tr_b16 v[222:223], v255 offset:0x3200
	ds_read_b64_tr_b16 v[224:225], v255 offset:0x3a00
	s_waitcnt lgkmcnt(0)
	v_mfma_f32_32x32x16_bf16 v[32:47], v[80:83], v[210:213], v[32:47]
	ds_read_b64_tr_b16 v[210:211], v255 offset:0x400
	ds_read_b64_tr_b16 v[212:213], v255 offset:0xc00
	v_mfma_f32_32x32x16_bf16 v[32:47], v[84:87], v[214:217], v[32:47]
	ds_read_b64_tr_b16 v[214:215], v255 offset:0x1400
	ds_read_b64_tr_b16 v[216:217], v255 offset:0x1c00
	v_mfma_f32_32x32x16_bf16 v[32:47], v[88:91], v[218:221], v[32:47]
	ds_read_b64_tr_b16 v[218:219], v255 offset:0x2400
	ds_read_b64_tr_b16 v[220:221], v255 offset:0x2c00
	v_mfma_f32_32x32x16_bf16 v[32:47], v[92:95], v[222:225], v[32:47]
	ds_read_b64_tr_b16 v[222:223], v255 offset:0x3400
	ds_read_b64_tr_b16 v[224:225], v255 offset:0x3c00
	s_waitcnt lgkmcnt(0)
	v_mfma_f32_32x32x16_bf16 v[48:63], v[80:83], v[210:213], v[48:63]
	ds_read_b64_tr_b16 v[210:211], v255 offset:0x600
	ds_read_b64_tr_b16 v[212:213], v255 offset:0xe00
	v_mfma_f32_32x32x16_bf16 v[48:63], v[84:87], v[214:217], v[48:63]
	ds_read_b64_tr_b16 v[214:215], v255 offset:0x1600
	ds_read_b64_tr_b16 v[216:217], v255 offset:0x1e00
	v_mfma_f32_32x32x16_bf16 v[48:63], v[88:91], v[218:221], v[48:63]
	ds_read_b64_tr_b16 v[218:219], v255 offset:0x2600
	ds_read_b64_tr_b16 v[220:221], v255 offset:0x2e00
	v_mfma_f32_32x32x16_bf16 v[48:63], v[92:95], v[222:225], v[48:63]
	ds_read_b64_tr_b16 v[222:223], v255 offset:0x3600
	ds_read_b64_tr_b16 v[224:225], v255 offset:0x3e00
	s_waitcnt lgkmcnt(0)
	v_mfma_f32_32x32x16_bf16 v[64:79], v[80:83], v[210:213], v[64:79]
	v_exp_f32_e32 v210, v112
	v_exp_f32_e32 v211, v113
	v_exp_f32_e32 v212, v114
	v_exp_f32_e32 v213, v115
	v_mfma_f32_32x32x16_bf16 v[64:79], v[84:87], v[214:217], v[64:79]
	v_exp_f32_e32 v214, v116
	v_exp_f32_e32 v215, v117
	v_exp_f32_e32 v216, v118
	v_exp_f32_e32 v217, v119
	v_mfma_f32_32x32x16_bf16 v[64:79], v[88:91], v[218:221], v[64:79]
	v_exp_f32_e32 v218, v120
	v_exp_f32_e32 v219, v121
	v_exp_f32_e32 v220, v122
	v_exp_f32_e32 v221, v123
	s_mov_b32 s100, vcc_lo
	s_mov_b32 vcc_lo, vcc_hi
	s_mov_b32 vcc_hi, s101
	s_mov_b32 s101, s100
	s_waitcnt lgkmcnt(0)
	s_barrier
	ds_read_b128 v[80:83], v200 offset:32768
	ds_read_b128 v[84:87], v200 offset:40960
	v_mfma_f32_32x32x16_bf16 v[64:79], v[92:95], v[222:225], v[64:79]
	ds_read_b128 v[160:163], v201 offset:32768
	ds_read_b128 v[164:167], v201 offset:40960
	ds_read_b128 v[168:171], v202 offset:32768
	ds_read_b128 v[172:175], v202 offset:40960
	ds_read_b128 v[188:191], v203 offset:32768
	ds_read_b128 v[192:195], v203 offset:40960
	v_exp_f32_e32 v222, v124
	v_exp_f32_e32 v223, v125
	v_exp_f32_e32 v224, v126
	v_exp_f32_e32 v225, v127
	v_exp_f32_e32 v104, v104
	v_exp_f32_e32 v105, v105
	v_exp_f32_e32 v106, v106
	v_exp_f32_e32 v107, v107
	v_exp_f32_e32 v108, v108
	v_exp_f32_e32 v109, v109
	v_exp_f32_e32 v110, v110
	v_exp_f32_e32 v111, v111
	s_waitcnt lgkmcnt(7)
	v_mfma_f32_32x32x16_bf16 v[112:127], v[80:83], v[156:159], 0
	s_waitcnt lgkmcnt(6)
	v_mfma_f32_32x32x16_bf16 v[80:95], v[84:87], v[156:159], 0
	s_waitcnt lgkmcnt(5)
	v_mfma_f32_32x32x16_bf16 v[112:127], v[160:163], v[152:155], v[112:127]
	s_waitcnt lgkmcnt(4)
	v_mfma_f32_32x32x16_bf16 v[80:95], v[164:167], v[152:155], v[80:95]
	ds_read_b128 v[160:163], v206 offset:32768
	ds_read_b128 v[164:167], v206 offset:40960
	s_waitcnt lgkmcnt(5)
	v_mfma_f32_32x32x16_bf16 v[112:127], v[168:171], v[148:151], v[112:127]
	s_waitcnt lgkmcnt(4)
	v_mfma_f32_32x32x16_bf16 v[80:95], v[172:175], v[148:151], v[80:95]
	ds_read_b128 v[168:171], v204 offset:32768
	ds_read_b128 v[172:175], v204 offset:40960
	s_waitcnt lgkmcnt(5)
	v_mfma_f32_32x32x16_bf16 v[112:127], v[188:191], v[144:147], v[112:127]
	s_waitcnt lgkmcnt(4)
	v_mfma_f32_32x32x16_bf16 v[80:95], v[192:195], v[144:147], v[80:95]
	ds_read_b128 v[188:191], v205 offset:32768
	ds_read_b128 v[192:195], v205 offset:40960
	v_add_u32_e32 v254, vcc_lo, v184
	v_add_u32_e32 v255, vcc_lo, v185
	s_waitcnt vmcnt(0)
	ds_write_b128 v254, v[2:5]
	s_waitcnt lgkmcnt(6)
	v_mfma_f32_32x32x16_bf16 v[112:127], v[160:163], v[140:143], v[112:127]
	s_waitcnt lgkmcnt(5)
	v_mfma_f32_32x32x16_bf16 v[80:95], v[164:167], v[140:143], v[80:95]
	ds_read_b128 v[160:163], v207 offset:32768
	ds_read_b128 v[164:167], v207 offset:40960
	ds_write_b128 v255, v[6:9]
	s_waitcnt lgkmcnt(7)
	v_mfma_f32_32x32x16_bf16 v[112:127], v[168:171], v[136:139], v[112:127]
	s_waitcnt lgkmcnt(6)
	v_mfma_f32_32x32x16_bf16 v[80:95], v[172:175], v[136:139], v[80:95]
	ds_write_b128 v198, v[10:13] offset:49152
	s_waitcnt lgkmcnt(6)
	v_mfma_f32_32x32x16_bf16 v[112:127], v[188:191], v[132:135], v[112:127]
	s_waitcnt lgkmcnt(5)
	v_mfma_f32_32x32x16_bf16 v[80:95], v[192:195], v[132:135], v[80:95]
	ds_write_b128 v199, v[176:179] offset:49152
	s_waitcnt lgkmcnt(4)
	v_mfma_f32_32x32x16_bf16 v[112:127], v[160:163], v[128:131], v[112:127]
	s_waitcnt lgkmcnt(3)
; #define SBAR() __builtin_amdgcn_sched_barrier(0)
; __device__ __forceinline__ void finishSM(f32x16& p0, f32x16& p1, float alpha, float& l_reg, bf16x8& pa0, bf16x8& pa1, bf16x8& pa2, bf16x8& pa3) {
; #pragma unroll
;   for (int r = 0; r < 16; ++r) p1[r] = __builtin_amdgcn_exp2f(p1[r]);
;   float ps = 0;
; #pragma unroll
;   for (int r = 0; r < 16; ++r) ps += p0[r];
; #pragma unroll
;   for (int r = 0; r < 16; ++r) ps += p1[r];
;   { auto rr = __builtin_amdgcn_permlane32_swap(__float_as_uint(ps), __float_as_uint(ps), false, false);
;     ps = __uint_as_float(rr[0]) + __uint_as_float(rr[1]); }
;   l_reg = l_reg * alpha + ps;
;     ...
;   PK4(p0, 0, pa0); PK4(p0, 8, pa1); PK4(p1, 0, pa2); PK4(p1, 8, pa3);
;     ...
; }
; template <int D0> __device__ __forceinline__ void pv_one(f32x16& od, int vb, bf16x8 pa0, bf16x8 pa1, bf16x8 pa2, bf16x8 pa3) {
;   const s16x4 l0 = tr_read<v_rd_off(D0, 0, 0)>(vb), h0 = tr_read<v_rd_off(D0, 0, 1)>(vb), l1 = tr_read<v_rd_off(D0, 1, 0)>(vb), h1 = tr_read<v_rd_off(D0, 1, 1)>(vb);
;   const s16x4 l2 = tr_read<v_rd_off(D0, 2, 0)>(vb), h2 = tr_read<v_rd_off(D0, 2, 1)>(vb), l3 = tr_read<v_rd_off(D0, 3, 0)>(vb), h3 = tr_read<v_rd_off(D0, 3, 1)>(vb);
;   asm volatile("s_waitcnt lgkmcnt(0)" ::: "memory"); SBAR();
;     ...
;   od = __builtin_amdgcn_mfma_f32_32x32x16_bf16(pa0, PK(l0, h0), od, 0, 0, 0);
;   od = __builtin_amdgcn_mfma_f32_32x32x16_bf16(pa1, PK(l1, h1), od, 0, 0, 0);
;   od = __builtin_amdgcn_mfma_f32_32x32x16_bf16(pa2, PK(l2, h2), od, 0, 0, 0);
;   od = __builtin_amdgcn_mfma_f32_32x32x16_bf16(pa3, PK(l3, h3), od, 0, 0, 0);
;     ...
; }
; __device__ __forceinline__ void pv_d0(f32x16* o, int vb, bf16x8 pa0, bf16x8 pa1, bf16x8 pa2, bf16x8 pa3) {
;   pv_one<0>(o[0], vb, pa0, pa1, pa2, pa3); pv_one<1>(o[1], vb, pa0, pa1, pa2, pa3); pv_one<2>(o[2], vb, pa0, pa1, pa2, pa3); pv_one<3>(o[3], vb, pa0, pa1, pa2, pa3);
; }
	v_mfma_f32_32x32x16_bf16 v[80:95], v[164:167], v[128:131], v[80:95]
	v_exp_f32_e32 v160, v96
	v_add_f32_e32 v96, 0, v210
	v_add_f32_e32 v96, v211, v96
	v_add_f32_e32 v96, v212, v96
	v_add_f32_e32 v96, v213, v96
	v_add_f32_e32 v96, v214, v96
	v_add_f32_e32 v96, v215, v96
	v_add_f32_e32 v96, v216, v96
	v_add_f32_e32 v96, v217, v96
	v_add_f32_e32 v96, v218, v96
	v_add_f32_e32 v96, v219, v96
	v_add_f32_e32 v96, v220, v96
	v_add_f32_e32 v96, v221, v96
	v_add_f32_e32 v96, v222, v96
	v_exp_f32_e32 v161, v97
	v_add_f32_e32 v96, v223, v96
	v_exp_f32_e32 v162, v98
	v_add_f32_e32 v96, v224, v96
	v_exp_f32_e32 v163, v99
	v_add_f32_e32 v96, v225, v96
	v_exp_f32_e32 v164, v100
	v_add_f32_e32 v96, v160, v96
	v_exp_f32_e32 v165, v101
	v_add_f32_e32 v96, v161, v96
	v_exp_f32_e32 v166, v102
	v_add_f32_e32 v96, v162, v96
	v_exp_f32_e32 v167, v103
	v_add_f32_e32 v96, v163, v96
	v_add_f32_e32 v96, v164, v96
	v_add_f32_e32 v96, v165, v96
	v_add_f32_e32 v96, v166, v96
	v_add_f32_e32 v96, v167, v96
	v_add_f32_e32 v96, v104, v96
	v_add_f32_e32 v96, v105, v96
	v_add_f32_e32 v96, v106, v96
	v_add_f32_e32 v96, v107, v96
	v_add_f32_e32 v96, v108, v96
	v_add_f32_e32 v96, v109, v96
	v_add_f32_e32 v96, v110, v96
	v_add_f32_e32 v96, v111, v96
	v_mov_b32_e32 v97, v96
	s_nop 1
	v_permlane32_swap_b32_e32 v96, v97
	v_add_f32_e32 v96, v96, v97
	v_add_f32_e32 v183, v226, v96
	v_cvt_pk_bf16_f32 v96, v210, v211
	v_cvt_pk_bf16_f32 v97, v212, v213
	v_cvt_pk_bf16_f32 v98, v214, v215
	v_cvt_pk_bf16_f32 v99, v216, v217
	v_cvt_pk_bf16_f32 v100, v218, v219
	v_cvt_pk_bf16_f32 v101, v220, v221
	v_cvt_pk_bf16_f32 v102, v222, v223
	v_cvt_pk_bf16_f32 v103, v224, v225
	v_cvt_pk_bf16_f32 v111, v110, v111
	v_cvt_pk_bf16_f32 v110, v108, v109
	v_cvt_pk_bf16_f32 v109, v106, v107
	v_cvt_pk_bf16_f32 v108, v104, v105
	v_cvt_pk_bf16_f32 v104, v160, v161
	v_cvt_pk_bf16_f32 v105, v162, v163
	v_cvt_pk_bf16_f32 v106, v164, v165
	v_cvt_pk_bf16_f32 v107, v166, v167
	v_permlane32_swap_b32_e32 v96, v98
	v_permlane32_swap_b32_e32 v97, v99
	v_permlane32_swap_b32_e32 v100, v102
	v_permlane32_swap_b32_e32 v101, v103
	v_permlane32_swap_b32_e32 v104, v106
	v_permlane32_swap_b32_e32 v105, v107
	v_permlane32_swap_b32_e32 v109, v111
	v_permlane32_swap_b32_e32 v108, v110
	s_min_u32 s40, s2, 0xfc
	s_add_i32 s100, s40, 3
	s_mul_i32 s100, s100, 0x60000
	v_add_u32_e32 v254, s100, v14
	v_add_u32_e32 v255, s100, v15
	global_load_dwordx4 v[160:163], v254, s[58:59]
	global_load_dwordx4 v[164:167], v255, s[58:59]
	global_load_dwordx4 v[168:171], v254, s[8:9]
	global_load_dwordx4 v[172:175], v255, s[8:9]
	v_add_u32_e32 v255, vcc_hi, v208
	ds_read_b64_tr_b16 v[210:211], v255 offset:0
	ds_read_b64_tr_b16 v[212:213], v255 offset:0x800
	ds_read_b64_tr_b16 v[214:215], v255 offset:0x1000
	ds_read_b64_tr_b16 v[216:217], v255 offset:0x1800
	ds_read_b64_tr_b16 v[218:219], v255 offset:0x2000
	ds_read_b64_tr_b16 v[220:221], v255 offset:0x2800
	ds_read_b64_tr_b16 v[222:223], v255 offset:0x3000
	ds_read_b64_tr_b16 v[224:225], v255 offset:0x3800
	s_waitcnt lgkmcnt(0)
	s_nop 0
	v_mfma_f32_32x32x16_bf16 v[16:31], v[96:99], v[210:213], v[16:31]
	ds_read_b64_tr_b16 v[210:211], v255 offset:0x200
	ds_read_b64_tr_b16 v[212:213], v255 offset:0xa00
	v_mfma_f32_32x32x16_bf16 v[16:31], v[100:103], v[214:217], v[16:31]
	ds_read_b64_tr_b16 v[214:215], v255 offset:0x1200
	ds_read_b64_tr_b16 v[216:217], v255 offset:0x1a00
	v_mfma_f32_32x32x16_bf16 v[16:31], v[104:107], v[218:221], v[16:31]
	ds_read_b64_tr_b16 v[218:219], v255 offset:0x2200
	ds_read_b64_tr_b16 v[220:221], v255 offset:0x2a00
	v_mfma_f32_32x32x16_bf16 v[16:31], v[108:111], v[222:225], v[16:31]
	ds_read_b64_tr_b16 v[222:223], v255 offset:0x3200
	ds_read_b64_tr_b16 v[224:225], v255 offset:0x3a00
	s_waitcnt lgkmcnt(0)
	v_mfma_f32_32x32x16_bf16 v[32:47], v[96:99], v[210:213], v[32:47]
	ds_read_b64_tr_b16 v[210:211], v255 offset:0x400
	ds_read_b64_tr_b16 v[212:213], v255 offset:0xc00
	v_mfma_f32_32x32x16_bf16 v[32:47], v[100:103], v[214:217], v[32:47]
	ds_read_b64_tr_b16 v[214:215], v255 offset:0x1400
	ds_read_b64_tr_b16 v[216:217], v255 offset:0x1c00
	v_mfma_f32_32x32x16_bf16 v[32:47], v[104:107], v[218:221], v[32:47]
	ds_read_b64_tr_b16 v[218:219], v255 offset:0x2400
	ds_read_b64_tr_b16 v[220:221], v255 offset:0x2c00
	v_mfma_f32_32x32x16_bf16 v[32:47], v[108:111], v[222:225], v[32:47]
	ds_read_b64_tr_b16 v[222:223], v255 offset:0x3400
	ds_read_b64_tr_b16 v[224:225], v255 offset:0x3c00
	s_waitcnt lgkmcnt(0)
	v_mfma_f32_32x32x16_bf16 v[48:63], v[96:99], v[210:213], v[48:63]
	ds_read_b64_tr_b16 v[210:211], v255 offset:0x600
	ds_read_b64_tr_b16 v[212:213], v255 offset:0xe00
	v_mfma_f32_32x32x16_bf16 v[48:63], v[100:103], v[214:217], v[48:63]
	ds_read_b64_tr_b16 v[214:215], v255 offset:0x1600
	ds_read_b64_tr_b16 v[216:217], v255 offset:0x1e00
	v_mfma_f32_32x32x16_bf16 v[48:63], v[104:107], v[218:221], v[48:63]
	ds_read_b64_tr_b16 v[218:219], v255 offset:0x2600
	ds_read_b64_tr_b16 v[220:221], v255 offset:0x2e00
	v_mfma_f32_32x32x16_bf16 v[48:63], v[108:111], v[222:225], v[48:63]
	ds_read_b64_tr_b16 v[222:223], v255 offset:0x3600
	ds_read_b64_tr_b16 v[224:225], v255 offset:0x3e00
	s_waitcnt lgkmcnt(0)
	v_mfma_f32_32x32x16_bf16 v[64:79], v[96:99], v[210:213], v[64:79]
	v_exp_f32_e32 v210, v124
	v_exp_f32_e32 v213, v125
	v_exp_f32_e32 v211, v126
	v_exp_f32_e32 v212, v127
	v_mfma_f32_32x32x16_bf16 v[64:79], v[100:103], v[214:217], v[64:79]
	v_exp_f32_e32 v215, v120
	v_exp_f32_e32 v217, v121
	v_exp_f32_e32 v214, v122
	v_exp_f32_e32 v216, v123
	s_cmpk_gt_u32 s2, 0xfc
	v_mfma_f32_32x32x16_bf16 v[64:79], v[104:107], v[218:221], v[64:79]
	v_exp_f32_e32 v221, v114
	v_exp_f32_e32 v220, v116
	v_exp_f32_e32 v218, v118
	v_exp_f32_e32 v219, v119
	s_mov_b32 s100, vcc_lo
	s_mov_b32 vcc_lo, vcc_hi
	s_mov_b32 vcc_hi, s101
	s_mov_b32 s101, s100
	s_waitcnt lgkmcnt(0)
	s_barrier
; #define SBAR() __builtin_amdgcn_sched_barrier(0)
; #define RESC(a) do { if (!FIXED && __any((a) < 1.f)) { if (hi == 0) al_l[r32] = (a); asm volatile("s_waitcnt lgkmcnt(0)" ::: "memory"); \
;     _Pragma("unroll") for (int d = 0; d < 4; ++d) _Pragma("unroll") for (int r = 0; r < 16; ++r) o[d][r] *= al_l[crow(r, hi)]; } } while (0)
; #define MASK(P0, P1, t) do { if (BANDED) band_mask(P0, P1, rel00 + (t) * KVBLK, mlo, mhi); } while (0)
; __device__ __forceinline__ void finishSM(f32x16& p0, f32x16& p1, float alpha, float& l_reg, bf16x8& pa0, bf16x8& pa1, bf16x8& pa2, bf16x8& pa3) {
; #pragma unroll
;   for (int r = 0; r < 16; ++r) p1[r] = __builtin_amdgcn_exp2f(p1[r]);
;   float ps = 0;
; #pragma unroll
;   for (int r = 0; r < 16; ++r) ps += p0[r];
; #pragma unroll
;   for (int r = 0; r < 16; ++r) ps += p1[r];
;   { auto rr = __builtin_amdgcn_permlane32_swap(__float_as_uint(ps), __float_as_uint(ps), false, false);
;     ps = __uint_as_float(rr[0]) + __uint_as_float(rr[1]); }
;   l_reg = l_reg * alpha + ps;
;     ...
;   PK4(p0, 0, pa0); PK4(p0, 8, pa1); PK4(p1, 0, pa2); PK4(p1, 8, pa3);
;     ...
; }
; template <bool BANDED, bool FIXED> ...
;     ...
;   SBAR(); if (FIXED) qkt_c(pB0, pB1, (bf16*)((char*)K_lds + SHM_K), qr, r32, hi); else qkt(pB0, pB1, (bf16*)((char*)K_lds + SHM_K), qr, r32, hi, 0.f); MASK(pB0, pB1, NT - 1);
;   finishSM(pA0, pA1, alA, l_reg, pa0, pa1, pa2, pa3); SBAR();
;   pv_d0(o, vb0, pa0, pa1, pa2, pa3); partialSM<FIXED, !BANDED>(pB0, pB1, m_reg, mnB, alB);
;   __syncthreads(); RESC(alB);
;   finishSM(pB0, pB1, alB, l_reg, pa0, pa1, pa2, pa3); SBAR();
;   pv_d0(o, vb0 + (int)SHM_V, pa0, pa1, pa2, pa3);
	ds_read_b128 v[2:5], v200 offset:49152
	ds_read_b128 v[6:9], v200 offset:57344
	v_mfma_f32_32x32x16_bf16 v[64:79], v[108:111], v[222:225], v[64:79]
	v_exp_f32_e32 v223, v112
	v_exp_f32_e32 v225, v113
	v_exp_f32_e32 v224, v115
	v_exp_f32_e32 v222, v117
	s_cbranch_scc0 .LBB0_118
	v_mov_b32_e32 v188, 0x3c0881c4
	v_mov_b32_e32 v189, 0xbab64f3b
	v_mov_b32_e32 v190, 1
	v_bfrev_b32_e32 v191, 0.5
	v_mov_b32_e32 v192, 0xf149f2ca
	v_mov_b32_e32 v193, 0xff800000
	v_mov_b32_e32 v194, 0x41b17218
	v_not_b32_e32 v195, 63
	v_add_u32_e32 v255, vcc_hi, v208
	v_add_u32_e32 v254, s101, v208
	v_exp_f32_e32 v12, v80
	v_exp_f32_e32 v13, v81
	v_exp_f32_e32 v14, v82
	s_waitcnt lgkmcnt(1)
	v_mfma_f32_32x32x16_bf16 v[112:127], v[2:5], v[156:159], 0
	v_exp_f32_e32 v15, v83
	v_exp_f32_e32 v80, v84
	v_exp_f32_e32 v81, v85
	v_exp_f32_e32 v82, v86
	v_exp_f32_e32 v83, v87
	v_exp_f32_e32 v84, v88
	v_exp_f32_e32 v85, v89
	s_waitcnt lgkmcnt(0)
	v_mfma_f32_32x32x16_bf16 v[96:111], v[6:9], v[156:159], 0
	ds_read_b128 v[2:5], v201 offset:49152
	ds_read_b128 v[6:9], v201 offset:57344
	v_exp_f32_e32 v86, v90
	v_exp_f32_e32 v87, v91
	v_exp_f32_e32 v88, v92
	v_exp_f32_e32 v89, v93
	v_exp_f32_e32 v90, v94
	v_exp_f32_e32 v91, v95
	s_waitcnt lgkmcnt(1)
	v_mfma_f32_32x32x16_bf16 v[112:127], v[2:5], v[152:155], v[112:127]
	v_cvt_pk_bf16_f32 v10, v210, v213
	v_cvt_pk_bf16_f32 v11, v211, v212
	s_waitcnt lgkmcnt(0)
	v_mfma_f32_32x32x16_bf16 v[96:111], v[6:9], v[152:155], v[96:111]
	ds_read_b128 v[2:5], v202 offset:49152
	ds_read_b128 v[6:9], v202 offset:57344
	s_waitcnt lgkmcnt(1)
	v_mfma_f32_32x32x16_bf16 v[112:127], v[2:5], v[148:151], v[112:127]
	s_waitcnt lgkmcnt(0)
	v_mfma_f32_32x32x16_bf16 v[96:111], v[6:9], v[148:151], v[96:111]
	ds_read_b128 v[2:5], v203 offset:49152
	ds_read_b128 v[6:9], v203 offset:57344
	s_waitcnt lgkmcnt(1)
	v_mfma_f32_32x32x16_bf16 v[112:127], v[2:5], v[144:147], v[112:127]
	s_waitcnt lgkmcnt(0)
	v_mfma_f32_32x32x16_bf16 v[96:111], v[6:9], v[144:147], v[96:111]
	ds_read_b128 v[2:5], v206 offset:49152
	ds_read_b128 v[6:9], v206 offset:57344
	s_waitcnt lgkmcnt(1)
	v_mfma_f32_32x32x16_bf16 v[112:127], v[2:5], v[140:143], v[112:127]
	s_waitcnt lgkmcnt(0)
	v_mfma_f32_32x32x16_bf16 v[96:111], v[6:9], v[140:143], v[96:111]
	ds_read_b128 v[2:5], v204 offset:49152
	ds_read_b128 v[6:9], v204 offset:57344
	s_waitcnt lgkmcnt(1)
	v_mfma_f32_32x32x16_bf16 v[112:127], v[2:5], v[136:139], v[112:127]
	s_waitcnt lgkmcnt(0)
	v_mfma_f32_32x32x16_bf16 v[96:111], v[6:9], v[136:139], v[96:111]
	ds_read_b128 v[2:5], v205 offset:49152
	ds_read_b128 v[6:9], v205 offset:57344
	s_waitcnt lgkmcnt(1)
	v_mfma_f32_32x32x16_bf16 v[112:127], v[2:5], v[132:135], v[112:127]
	s_waitcnt lgkmcnt(0)
	v_mfma_f32_32x32x16_bf16 v[96:111], v[6:9], v[132:135], v[96:111]
	ds_read_b128 v[2:5], v207 offset:49152
	ds_read_b128 v[6:9], v207 offset:57344
	s_waitcnt lgkmcnt(1)
	v_mfma_f32_32x32x16_bf16 v[112:127], v[2:5], v[128:131], v[112:127]
	v_add_f32_e32 v2, 0, v223
	v_add_f32_e32 v2, v225, v2
	v_add_f32_e32 v2, v221, v2
	v_add_f32_e32 v2, v224, v2
	v_add_f32_e32 v2, v220, v2
	v_add_f32_e32 v2, v222, v2
	v_add_f32_e32 v2, v218, v2
	v_add_f32_e32 v2, v219, v2
	v_add_f32_e32 v2, v215, v2
	v_add_f32_e32 v2, v217, v2
	v_add_f32_e32 v2, v214, v2
	v_add_f32_e32 v2, v216, v2
	v_add_f32_e32 v2, v210, v2
	v_add_f32_e32 v2, v213, v2
	v_add_f32_e32 v2, v211, v2
	v_add_f32_e32 v2, v212, v2
	v_add_f32_e32 v2, v12, v2
	v_add_f32_e32 v2, v13, v2
	v_add_f32_e32 v2, v14, v2
	v_add_f32_e32 v2, v15, v2
	v_add_f32_e32 v2, v80, v2
	v_add_f32_e32 v2, v81, v2
	v_add_f32_e32 v2, v82, v2
	v_add_f32_e32 v2, v83, v2
	v_add_f32_e32 v2, v84, v2
	v_add_f32_e32 v2, v85, v2
	v_add_f32_e32 v2, v86, v2
	v_add_f32_e32 v2, v87, v2
	v_add_f32_e32 v2, v88, v2
	v_add_f32_e32 v2, v89, v2
	v_add_f32_e32 v2, v90, v2
	v_add_f32_e32 v2, v91, v2
	s_waitcnt lgkmcnt(0)
	v_mfma_f32_32x32x16_bf16 v[96:111], v[6:9], v[128:131], v[96:111]
	v_mov_b32_e32 v3, v2
	v_cvt_pk_bf16_f32 v4, v223, v225
	v_cvt_pk_bf16_f32 v5, v221, v224
	v_cvt_pk_bf16_f32 v6, v220, v222
	v_cvt_pk_bf16_f32 v7, v218, v219
	s_nop 1
	v_permlane32_swap_b32_e32 v2, v3
	v_permlane32_swap_b32_e32 v4, v6
	v_permlane32_swap_b32_e32 v5, v7
	v_cvt_pk_bf16_f32 v8, v215, v217
	v_cvt_pk_bf16_f32 v9, v214, v216
	v_cvt_pk_bf16_f32 v12, v12, v13
	v_cvt_pk_bf16_f32 v13, v14, v15
	v_cvt_pk_bf16_f32 v14, v80, v81
	v_cvt_pk_bf16_f32 v15, v82, v83
	v_cvt_pk_bf16_f32 v80, v84, v85
	v_cvt_pk_bf16_f32 v81, v86, v87
	v_cvt_pk_bf16_f32 v82, v88, v89
	v_cvt_pk_bf16_f32 v83, v90, v91
	s_nop 0
	v_permlane32_swap_b32_e32 v8, v10
	v_permlane32_swap_b32_e32 v9, v11
	v_permlane32_swap_b32_e32 v12, v14
	v_permlane32_swap_b32_e32 v13, v15
	v_permlane32_swap_b32_e32 v80, v82
	v_permlane32_swap_b32_e32 v81, v83
	ds_read_b64_tr_b16 v[84:85], v255 offset:0
	ds_read_b64_tr_b16 v[86:87], v255 offset:0x800
	ds_read_b64_tr_b16 v[88:89], v255 offset:0x1000
	ds_read_b64_tr_b16 v[90:91], v255 offset:0x1800
	ds_read_b64_tr_b16 v[92:93], v255 offset:0x2000
	ds_read_b64_tr_b16 v[94:95], v255 offset:0x2800
	ds_read_b64_tr_b16 v[128:129], v255 offset:0x3000
	ds_read_b64_tr_b16 v[130:131], v255 offset:0x3800
	s_waitcnt lgkmcnt(0)
	s_nop 0
	v_mfma_f32_32x32x16_bf16 v[16:31], v[4:7], v[84:87], v[16:31]
	ds_read_b64_tr_b16 v[84:85], v255 offset:0x200
	ds_read_b64_tr_b16 v[86:87], v255 offset:0xa00
	v_mfma_f32_32x32x16_bf16 v[16:31], v[8:11], v[88:91], v[16:31]
	ds_read_b64_tr_b16 v[88:89], v255 offset:0x1200
	ds_read_b64_tr_b16 v[90:91], v255 offset:0x1a00
	v_mfma_f32_32x32x16_bf16 v[16:31], v[12:15], v[92:95], v[16:31]
	ds_read_b64_tr_b16 v[92:93], v255 offset:0x2200
	ds_read_b64_tr_b16 v[94:95], v255 offset:0x2a00
	v_mfma_f32_32x32x16_bf16 v[16:31], v[80:83], v[128:131], v[16:31]
	ds_read_b64_tr_b16 v[128:129], v255 offset:0x3200
	ds_read_b64_tr_b16 v[130:131], v255 offset:0x3a00
	s_waitcnt lgkmcnt(0)
; #define SBAR() __builtin_amdgcn_sched_barrier(0)
; #define RESC(a) do { if (!FIXED && __any((a) < 1.f)) { if (hi == 0) al_l[r32] = (a); asm volatile("s_waitcnt lgkmcnt(0)" ::: "memory"); \
;     _Pragma("unroll") for (int d = 0; d < 4; ++d) _Pragma("unroll") for (int r = 0; r < 16; ++r) o[d][r] *= al_l[crow(r, hi)]; } } while (0)
; #define MASK(P0, P1, t) do { if (BANDED) band_mask(P0, P1, rel00 + (t) * KVBLK, mlo, mhi); } while (0)
; template <bool BANDED, bool FIXED> ...
;     ...
;   SBAR(); if (FIXED) qkt_c(pB0, pB1, (bf16*)((char*)K_lds + SHM_K), qr, r32, hi); else qkt(pB0, pB1, (bf16*)((char*)K_lds + SHM_K), qr, r32, hi, 0.f); MASK(pB0, pB1, NT - 1);
;   finishSM(pA0, pA1, alA, l_reg, pa0, pa1, pa2, pa3); SBAR();
;   pv_d0(o, vb0, pa0, pa1, pa2, pa3); partialSM<FIXED, !BANDED>(pB0, pB1, m_reg, mnB, alB);
;   __syncthreads(); RESC(alB);
;   finishSM(pB0, pB1, alB, l_reg, pa0, pa1, pa2, pa3); SBAR();
;   pv_d0(o, vb0 + (int)SHM_V, pa0, pa1, pa2, pa3);
;   if (!BANDED && wave >= 4) __builtin_amdgcn_s_setprio(0);
	v_mfma_f32_32x32x16_bf16 v[32:47], v[4:7], v[84:87], v[32:47]
	ds_read_b64_tr_b16 v[84:85], v255 offset:0x400
	ds_read_b64_tr_b16 v[86:87], v255 offset:0xc00
	v_mfma_f32_32x32x16_bf16 v[32:47], v[8:11], v[88:91], v[32:47]
	ds_read_b64_tr_b16 v[88:89], v255 offset:0x1400
	ds_read_b64_tr_b16 v[90:91], v255 offset:0x1c00
	v_mfma_f32_32x32x16_bf16 v[32:47], v[12:15], v[92:95], v[32:47]
	ds_read_b64_tr_b16 v[92:93], v255 offset:0x2400
	ds_read_b64_tr_b16 v[94:95], v255 offset:0x2c00
	v_mfma_f32_32x32x16_bf16 v[32:47], v[80:83], v[128:131], v[32:47]
	ds_read_b64_tr_b16 v[128:129], v255 offset:0x3400
	ds_read_b64_tr_b16 v[130:131], v255 offset:0x3c00
	s_waitcnt lgkmcnt(0)
	v_mfma_f32_32x32x16_bf16 v[48:63], v[4:7], v[84:87], v[48:63]
	ds_read_b64_tr_b16 v[84:85], v255 offset:0x600
	ds_read_b64_tr_b16 v[86:87], v255 offset:0xe00
	v_mfma_f32_32x32x16_bf16 v[48:63], v[8:11], v[88:91], v[48:63]
	ds_read_b64_tr_b16 v[88:89], v255 offset:0x1600
	ds_read_b64_tr_b16 v[90:91], v255 offset:0x1e00
	v_mfma_f32_32x32x16_bf16 v[48:63], v[12:15], v[92:95], v[48:63]
	ds_read_b64_tr_b16 v[92:93], v255 offset:0x2600
	ds_read_b64_tr_b16 v[94:95], v255 offset:0x2e00
	v_mfma_f32_32x32x16_bf16 v[48:63], v[80:83], v[128:131], v[48:63]
	ds_read_b64_tr_b16 v[128:129], v255 offset:0x3600
	ds_read_b64_tr_b16 v[130:131], v255 offset:0x3e00
	s_waitcnt lgkmcnt(0)
	v_mfma_f32_32x32x16_bf16 v[64:79], v[4:7], v[84:87], v[64:79]
	v_exp_f32_e32 v6, v112
	v_exp_f32_e32 v7, v113
	v_exp_f32_e32 v84, v126
	v_exp_f32_e32 v85, v127
	v_add_f32_e32 v4, 0, v6
	v_add_f32_e32 v4, v7, v4
	v_exp_f32_e32 v86, v96
	v_mfma_f32_32x32x16_bf16 v[64:79], v[8:11], v[88:91], v[64:79]
	v_exp_f32_e32 v8, v114
	v_exp_f32_e32 v9, v115
	v_exp_f32_e32 v10, v116
	v_exp_f32_e32 v11, v117
	v_add_f32_e32 v4, v8, v4
	v_add_f32_e32 v4, v9, v4
	v_add_f32_e32 v4, v10, v4
	v_mfma_f32_32x32x16_bf16 v[64:79], v[12:15], v[92:95], v[64:79]
	v_exp_f32_e32 v12, v118
	v_exp_f32_e32 v13, v119
	v_exp_f32_e32 v14, v120
	v_exp_f32_e32 v15, v121
	v_add_f32_e32 v4, v11, v4
	v_add_f32_e32 v4, v12, v4
	v_add_f32_e32 v4, v13, v4
	v_mfma_f32_32x32x16_bf16 v[64:79], v[80:83], v[128:131], v[64:79]
	v_exp_f32_e32 v80, v122
	v_exp_f32_e32 v81, v123
	v_exp_f32_e32 v82, v124
	v_add_f32_e32 v4, v14, v4
	v_exp_f32_e32 v83, v125
	v_add_f32_e32 v4, v15, v4
	v_add_f32_e32 v4, v80, v4
	v_add_f32_e32 v4, v81, v4
	v_add_f32_e32 v4, v82, v4
	v_exp_f32_e32 v87, v97
	v_add_f32_e32 v4, v83, v4
	v_exp_f32_e32 v88, v98
	v_add_f32_e32 v4, v84, v4
	v_exp_f32_e32 v89, v99
	v_add_f32_e32 v4, v85, v4
	v_exp_f32_e32 v90, v100
	v_add_f32_e32 v4, v86, v4
	v_exp_f32_e32 v91, v101
	v_add_f32_e32 v4, v87, v4
	v_exp_f32_e32 v92, v102
	v_add_f32_e32 v4, v88, v4
	v_exp_f32_e32 v93, v103
	v_add_f32_e32 v4, v89, v4
	v_exp_f32_e32 v94, v104
	v_add_f32_e32 v4, v90, v4
	v_exp_f32_e32 v95, v105
	v_add_f32_e32 v4, v91, v4
	v_exp_f32_e32 v96, v106
	v_add_f32_e32 v4, v92, v4
	v_exp_f32_e32 v97, v107
	v_add_f32_e32 v4, v93, v4
	v_exp_f32_e32 v98, v108
	v_add_f32_e32 v4, v94, v4
	v_exp_f32_e32 v99, v109
	v_add_f32_e32 v4, v95, v4
	v_exp_f32_e32 v100, v110
	v_add_f32_e32 v4, v96, v4
	v_exp_f32_e32 v101, v111
	v_add_f32_e32 v4, v97, v4
	v_add_f32_e32 v4, v98, v4
	v_add_f32_e32 v4, v99, v4
	v_add_f32_e32 v4, v100, v4
	v_add_f32_e32 v4, v101, v4
	v_mov_b32_e32 v5, v4
	s_nop 1
	v_permlane32_swap_b32_e32 v4, v5
	v_cvt_pk_bf16_f32 v6, v6, v7
	v_cvt_pk_bf16_f32 v7, v8, v9
	v_cvt_pk_bf16_f32 v8, v10, v11
	v_cvt_pk_bf16_f32 v9, v12, v13
	v_cvt_pk_bf16_f32 v10, v14, v15
	v_cvt_pk_bf16_f32 v11, v80, v81
	v_cvt_pk_bf16_f32 v12, v82, v83
	v_cvt_pk_bf16_f32 v13, v84, v85
	v_cvt_pk_bf16_f32 v80, v86, v87
	v_cvt_pk_bf16_f32 v81, v88, v89
	v_cvt_pk_bf16_f32 v82, v90, v91
	v_cvt_pk_bf16_f32 v83, v92, v93
	v_cvt_pk_bf16_f32 v84, v94, v95
	v_cvt_pk_bf16_f32 v85, v96, v97
	v_cvt_pk_bf16_f32 v86, v98, v99
	v_cvt_pk_bf16_f32 v87, v100, v101
	s_barrier
	v_permlane32_swap_b32_e32 v6, v8
	v_permlane32_swap_b32_e32 v7, v9
	v_permlane32_swap_b32_e32 v10, v12
	v_permlane32_swap_b32_e32 v11, v13
	v_permlane32_swap_b32_e32 v80, v82
	v_permlane32_swap_b32_e32 v81, v83
	v_permlane32_swap_b32_e32 v84, v86
	v_permlane32_swap_b32_e32 v85, v87
	ds_read_b64_tr_b16 v[88:89], v254 offset:0
	ds_read_b64_tr_b16 v[90:91], v254 offset:0x800
	ds_read_b64_tr_b16 v[92:93], v254 offset:0x1000
	ds_read_b64_tr_b16 v[94:95], v254 offset:0x1800
	ds_read_b64_tr_b16 v[96:97], v254 offset:0x2000
	ds_read_b64_tr_b16 v[98:99], v254 offset:0x2800
	ds_read_b64_tr_b16 v[100:101], v254 offset:0x3000
	ds_read_b64_tr_b16 v[102:103], v254 offset:0x3800
	s_waitcnt lgkmcnt(0)
	s_nop 0
	v_mfma_f32_32x32x16_bf16 v[16:31], v[6:9], v[88:91], v[16:31]
	ds_read_b64_tr_b16 v[88:89], v254 offset:0x200
	ds_read_b64_tr_b16 v[90:91], v254 offset:0xa00
	v_mfma_f32_32x32x16_bf16 v[16:31], v[10:13], v[92:95], v[16:31]
	ds_read_b64_tr_b16 v[92:93], v254 offset:0x1200
	ds_read_b64_tr_b16 v[94:95], v254 offset:0x1a00
	v_mfma_f32_32x32x16_bf16 v[16:31], v[80:83], v[96:99], v[16:31]
	ds_read_b64_tr_b16 v[96:97], v254 offset:0x2200
	ds_read_b64_tr_b16 v[98:99], v254 offset:0x2a00
	v_mfma_f32_32x32x16_bf16 v[16:31], v[84:87], v[100:103], v[16:31]
	ds_read_b64_tr_b16 v[100:101], v254 offset:0x3200
	ds_read_b64_tr_b16 v[102:103], v254 offset:0x3a00
	s_waitcnt lgkmcnt(0)
	v_mfma_f32_32x32x16_bf16 v[32:47], v[6:9], v[88:91], v[32:47]
	ds_read_b64_tr_b16 v[88:89], v254 offset:0x400
	ds_read_b64_tr_b16 v[90:91], v254 offset:0xc00
	v_mfma_f32_32x32x16_bf16 v[32:47], v[10:13], v[92:95], v[32:47]
	ds_read_b64_tr_b16 v[92:93], v254 offset:0x1400
	ds_read_b64_tr_b16 v[94:95], v254 offset:0x1c00
	v_mfma_f32_32x32x16_bf16 v[32:47], v[80:83], v[96:99], v[32:47]
	ds_read_b64_tr_b16 v[96:97], v254 offset:0x2400
	ds_read_b64_tr_b16 v[98:99], v254 offset:0x2c00
	v_mfma_f32_32x32x16_bf16 v[32:47], v[84:87], v[100:103], v[32:47]
	ds_read_b64_tr_b16 v[100:101], v254 offset:0x3400
	ds_read_b64_tr_b16 v[102:103], v254 offset:0x3c00
	s_waitcnt lgkmcnt(0)
	v_mfma_f32_32x32x16_bf16 v[48:63], v[6:9], v[88:91], v[48:63]
	ds_read_b64_tr_b16 v[88:89], v254 offset:0x600
	ds_read_b64_tr_b16 v[90:91], v254 offset:0xe00
	v_mfma_f32_32x32x16_bf16 v[48:63], v[10:13], v[92:95], v[48:63]
	ds_read_b64_tr_b16 v[92:93], v254 offset:0x1600
	ds_read_b64_tr_b16 v[94:95], v254 offset:0x1e00
	v_mfma_f32_32x32x16_bf16 v[48:63], v[80:83], v[96:99], v[48:63]
	ds_read_b64_tr_b16 v[96:97], v254 offset:0x2600
	ds_read_b64_tr_b16 v[98:99], v254 offset:0x2e00
	v_mfma_f32_32x32x16_bf16 v[48:63], v[84:87], v[100:103], v[48:63]
	ds_read_b64_tr_b16 v[100:101], v254 offset:0x3600
	ds_read_b64_tr_b16 v[102:103], v254 offset:0x3e00
	s_waitcnt lgkmcnt(0)
	v_mfma_f32_32x32x16_bf16 v[64:79], v[6:9], v[88:91], v[64:79]
	s_and_b64 vcc, exec, s[22:23]
	v_mfma_f32_32x32x16_bf16 v[64:79], v[10:13], v[92:95], v[64:79]
	v_mfma_f32_32x32x16_bf16 v[64:79], v[80:83], v[96:99], v[64:79]
	v_mfma_f32_32x32x16_bf16 v[64:79], v[84:87], v[100:103], v[64:79]
	s_cbranch_vccz .LBB0_121
	s_setprio 0
